# attention K-tile top: next-tile scalar bookkeeping ahead of the barrier, V pieces reuse M0 (+0x3400), wave-0-only staging tail tested with a scalar compare
# speedup vs baseline: 1.0082x; 1.0016x over previous
.LBB0_835:
	s_waitcnt vmcnt(0)
	s_add_i32 s88, s34, 1
	s_lshl_b32 s89, s88, 6
	s_add_u32 s28, s56, s89
	s_addc_u32 s29, s57, 0
	s_bitcmp1_b32 s88, 0
	s_cselect_b32 s35, 0x5800, 0
	s_cmp_ge_u32 s88, s87
	s_waitcnt lgkmcnt(0)
	s_barrier
	s_cbranch_scc1 .LBB0_881
	s_cmp_lg_u32 s88, 1
	s_cbranch_scc1 .Lhwat0_fast
	s_and_saveexec_b64 s[66:67], s[4:5]
	s_cbranch_execnz .LBB0_840
	s_or_b64 exec, exec, s[66:67]
	s_and_saveexec_b64 s[66:67], s[6:7]
	s_cbranch_execnz .LBB0_849

.Lhwat0_fast:
	s_mov_b64 s[68:69], 0x80
	s_add_u32 m0, s98, s35
	v_lshl_add_u64 v[152:153], v[152:153], 0, v[154:155]
	global_load_lds_dwordx4 v[152:153], off
	s_add_u32 m0, m0, 0x3400
	v_lshl_add_u64 v[176:177], v[176:177], 0, s[68:69]
	global_load_lds_dwordx4 v[176:177], off
	s_add_u32 m0, s99, s35
	v_lshl_add_u64 v[158:159], v[158:159], 0, v[160:161]
	global_load_lds_dwordx4 v[158:159], off
	s_add_u32 m0, m0, 0x3400
	v_lshl_add_u64 v[180:181], v[180:181], 0, s[68:69]
	global_load_lds_dwordx4 v[180:181], off
	s_add_u32 m0, s100, s35
	v_lshl_add_u64 v[164:165], v[164:165], 0, v[166:167]
	global_load_lds_dwordx4 v[164:165], off
	s_cmp_lg_u64 s[10:11], 0
	s_cbranch_scc0 .Lhwat0_tail
	s_add_u32 m0, m0, 0x3400
	v_lshl_add_u64 v[148:149], v[148:149], 0, s[68:69]
	global_load_lds_dwordx4 v[148:149], off
	s_add_u32 m0, s101, s35
	v_lshl_add_u64 v[170:171], v[170:171], 0, v[172:173]
	global_load_lds_dwordx4 v[170:171], off
.Lhwat0_tail:
.LBB0_881:
	s_bitcmp1_b32 s34, 0
	s_cselect_b32 s28, 0x5800, 0
	v_or_b32_e32 v201, s28, v144
	s_mov_b32 s68, 0
	v_add_u32_e32 v202, v201, v198
	s_mov_b64 s[66:67], -1
	s_and_b64 vcc, exec, s[62:63]
	v_lshl_or_b32 v203, s68, 5, v190
	s_mov_b64 s[28:29], -1
	s_cbranch_vccnz .LBB0_883

.LBB0_2069:
	s_waitcnt vmcnt(0)
	s_add_i32 s87, s88, 1
	s_lshl_b32 s90, s87, 6
	s_add_u32 s34, s56, s90
	s_addc_u32 s35, s57, 0
	s_bitcmp1_b32 s87, 0
	s_cselect_b32 s89, 0x5800, 0
	s_cmp_ge_u32 s87, s86
	s_waitcnt lgkmcnt(0)
	s_barrier
	s_cbranch_scc1 .LBB0_2115
	s_cmp_lg_u32 s87, 1
	s_cbranch_scc1 .Lhwat1_fast
	s_and_saveexec_b64 s[66:67], s[6:7]
	s_cbranch_execnz .LBB0_2074
	s_or_b64 exec, exec, s[66:67]
	s_and_saveexec_b64 s[66:67], s[8:9]
	s_cbranch_execnz .LBB0_2083

.Lhwat1_fast:
	s_mov_b64 s[68:69], 0x80
	s_add_u32 m0, s98, s89
	v_lshl_add_u64 v[152:153], v[152:153], 0, v[154:155]
	global_load_lds_dwordx4 v[152:153], off
	s_add_u32 m0, m0, 0x3400
	v_lshl_add_u64 v[176:177], v[176:177], 0, s[68:69]
	global_load_lds_dwordx4 v[176:177], off
	s_add_u32 m0, s99, s89
	v_lshl_add_u64 v[158:159], v[158:159], 0, v[160:161]
	global_load_lds_dwordx4 v[158:159], off
	s_add_u32 m0, m0, 0x3400
	v_lshl_add_u64 v[180:181], v[180:181], 0, s[68:69]
	global_load_lds_dwordx4 v[180:181], off
	s_add_u32 m0, s100, s89
	v_lshl_add_u64 v[164:165], v[164:165], 0, v[166:167]
	global_load_lds_dwordx4 v[164:165], off
	s_cmp_lg_u64 s[12:13], 0
	s_cbranch_scc0 .Lhwat1_tail
	s_add_u32 m0, m0, 0x3400
	v_lshl_add_u64 v[148:149], v[148:149], 0, s[68:69]
	global_load_lds_dwordx4 v[148:149], off
	s_add_u32 m0, s101, s89
	v_lshl_add_u64 v[170:171], v[170:171], 0, v[172:173]
	global_load_lds_dwordx4 v[170:171], off
.Lhwat1_tail:
.LBB0_2115:
	s_bitcmp1_b32 s88, 0
	s_cselect_b32 s30, 0x5800, 0
	v_or_b32_e32 v201, s30, v144
	s_mov_b32 s68, 0
	v_add_u32_e32 v202, v201, v198
	s_mov_b64 s[66:67], -1
	s_and_b64 vcc, exec, s[62:63]
	v_lshl_or_b32 v203, s68, 5, v190
	s_mov_b64 s[34:35], -1
	s_cbranch_vccnz .LBB0_2117
